# SSD staging: second round of chunk rows requested while the first round is transposed into LDS
# baseline (speedup 1.0000x reference)
.LBB0_35:
	s_mov_b32 s44, 0
	s_add_i32 s2, s44, s76
	s_waitcnt vmcnt(0)
	v_mbcnt_lo_u32_b32 v0, -1, 0
	v_mbcnt_hi_u32_b32 v0, -1, v0
	s_add_i32 s18, s44, s69
	v_lshl_add_u32 v176, s2, 6, v0
	s_add_i32 s82, s44, s72
	v_readfirstlane_b32 s2, v176
	s_ashr_i32 s6, s2, 6
	v_readlane_b32 s4, v254, 11
	s_cmp_gt_u32 s4, 16
	s_cselect_b64 s[2:3], -1, 0
	s_cmp_lt_u32 s4, 17
	s_cselect_b64 s[10:11], -1, 0
	s_and_b64 s[4:5], s[10:11], exec
	s_mov_b32 s4, 0x12000
	s_cselect_b32 s4, s4, 0x10000
	s_lshl_b32 s5, s82, 3
	s_abs_i32 s7, s5
	v_cvt_f32_u32_e32 v1, s7
	s_mov_b32 s14, s18
	v_writelane_b32 v254, s14, 41
	s_lshl_b32 s13, s18, 3
	v_rcp_iflag_f32_e32 v1, v1
	v_writelane_b32 v254, s15, 42
	s_add_i32 s6, s6, s13
	s_sub_i32 s13, 0, s7
	v_mul_f32_e32 v1, 0x4f7ffffe, v1
	v_cvt_u32_f32_e32 v1, v1
	s_add_i32 s12, s4, s5
	s_add_i32 s12, s12, -1
	s_xor_b32 s5, s12, s5
	v_readfirstlane_b32 s14, v1
	s_mul_i32 s13, s13, s14
	s_mul_hi_u32 s13, s14, s13
	s_abs_i32 s12, s12
	s_add_i32 s14, s14, s13
	s_mul_hi_u32 s13, s12, s14
	s_mul_i32 s14, s13, s7
	s_sub_i32 s12, s12, s14
	s_ashr_i32 s5, s5, 31
	s_add_i32 s14, s13, 1
	s_sub_i32 s15, s12, s7
	s_cmp_ge_u32 s12, s7
	s_cselect_b32 s13, s14, s13
	s_cselect_b32 s12, s15, s12
	s_add_i32 s14, s13, 1
	s_cmp_ge_u32 s12, s7
	s_cselect_b32 s7, s14, s13
	s_xor_b32 s7, s7, s5
	s_sub_i32 s5, s7, s5
	s_mul_i32 s56, s5, s6
	s_add_i32 s5, s56, s5
	s_min_i32 s57, s5, s4
	s_cmp_ge_i32 s56, s57
	s_mov_b32 s54, 0x800000
	s_cbranch_scc1 .LBB0_134
	v_readlane_b32 s28, v254, 11
	s_cmp_lg_u32 s28, 21
	s_cselect_b64 s[6:7], -1, 0
	s_cmp_eq_u32 s28, 21
	s_cselect_b64 s[12:13], -1, 0
	s_cmp_eq_u32 s28, 17
	s_cselect_b64 s[14:15], -1, 0
	s_lshl_b64 s[4:5], s[44:45], 3
	s_add_u32 s22, s70, s4
	v_readlane_b32 s24, v253, 62
	s_addc_u32 s23, s71, s5
	v_readlane_b32 s26, v254, 0
	v_readlane_b32 s27, v254, 1
	s_add_u32 s4, s26, s44
	s_addc_u32 s5, s27, 0
	s_lshl_b64 s[18:19], s[44:45], 2
	v_readlane_b32 s25, v253, 63
	s_add_u32 s58, s24, s18
	s_addc_u32 s59, s25, s19
	s_cmp_eq_u32 s28, 10
	s_cselect_b64 s[18:19], -1, 0
	s_and_b64 s[20:21], s[18:19], exec
	s_movk_i32 s20, 0x400
	s_cselect_b32 s60, s20, 0x1000
	s_cselect_b32 s61, 0, 0xc00
	s_or_b64 s[12:13], s[18:19], s[12:13]
	s_and_b64 s[18:19], s[12:13], exec
	s_cselect_b32 s18, 64, 48
	s_add_u32 s18, s22, s18
	s_addc_u32 s19, s23, 0
	s_load_dwordx2 s[18:19], s[18:19], 0x0
	s_and_b64 s[10:11], s[10:11], exec
	s_cselect_b32 s20, 0, 0x1000
	v_and_b32_e32 v34, 63, v0
	v_lshlrev_b32_e32 v192, 5, v34
	s_waitcnt lgkmcnt(0)
	s_add_u32 s10, s18, s20
	s_addc_u32 s11, s19, 0
	s_and_b64 s[12:13], s[12:13], exec
	s_cselect_b32 s12, 0x48, 56
	s_add_u32 s12, s22, s12
	s_addc_u32 s13, s23, 0
	s_load_dwordx2 s[12:13], s[12:13], 0x0
	v_xor_b32_e32 v32, 1, v229
	v_cmp_lt_i32_e32 vcc, v32, v231
	v_mov_b32_e32 v33, v193
	v_mov_b32_e32 v62, 0
	s_waitcnt lgkmcnt(0)
	s_add_u32 s12, s12, s20
	s_addc_u32 s13, s13, 0
	global_load_dwordx4 v[0:3], v192, s[10:11] offset:16
	global_load_dwordx4 v[4:7], v192, s[10:11]
	global_load_dwordx4 v[8:11], v192, s[12:13] offset:16
	global_load_dwordx4 v[12:15], v192, s[12:13]
	global_load_dwordx4 v[16:19], v192, s[10:11] offset:2064
	global_load_dwordx4 v[20:23], v192, s[10:11] offset:2048
	global_load_dwordx4 v[24:27], v192, s[12:13] offset:2064
	global_load_dwordx4 v[28:31], v192, s[12:13] offset:2048
	v_cndmask_b32_e32 v32, v229, v32, vcc
	v_lshlrev_b32_e32 v109, 2, v32
	v_xor_b32_e32 v32, 2, v229
	v_cmp_lt_i32_e32 vcc, v32, v231
	s_cmp_eq_u32 s28, 6
	s_cselect_b64 s[10:11], -1, 0
	v_cndmask_b32_e32 v32, v229, v32, vcc
	v_lshlrev_b32_e32 v121, 2, v32
	v_xor_b32_e32 v32, 4, v229
	v_cmp_lt_i32_e32 vcc, v32, v231
	s_and_b64 s[12:13], s[10:11], exec
	s_mov_b32 s12, 0x44d4000
	v_cndmask_b32_e32 v32, v229, v32, vcc
	v_lshlrev_b32_e32 v122, 2, v32
	v_xor_b32_e32 v32, 8, v229
	v_cmp_lt_i32_e32 vcc, v32, v231
	s_cselect_b32 s12, s12, 0x459a000
	s_or_b64 s[10:11], s[10:11], s[14:15]
	v_cndmask_b32_e32 v32, v229, v32, vcc
	v_lshlrev_b32_e32 v123, 2, v32
	v_xor_b32_e32 v32, 16, v229
	v_cmp_lt_i32_e32 vcc, v32, v231
	s_add_u32 s62, s4, 0x38260000
	s_addc_u32 s63, s5, 0
	v_cndmask_b32_e32 v32, v229, v32, vcc
	v_lshlrev_b32_e32 v124, 2, v32
	v_xor_b32_e32 v32, 32, v229
	s_add_u32 s64, s4, 0x3d2e4000
	v_cmp_lt_i32_e32 vcc, v32, v231
	s_addc_u32 s65, s5, 0
	s_add_u32 s14, s4, s12
	v_cndmask_b32_e32 v32, v229, v32, vcc
	v_lshlrev_b32_e32 v125, 2, v32
	v_lshlrev_b32_e32 v32, 4, v34
	s_addc_u32 s15, s5, 0
	v_lshl_add_u64 v[32:33], s[4:5], 0, v[32:33]
	s_mov_b64 s[4:5], 0x4660000
	v_lshl_add_u64 v[110:111], v[32:33], 0, s[4:5]
	v_cmp_eq_u32_e32 vcc, 0, v34
	s_mov_b64 s[4:5], 0x16660000
	v_lshlrev_b32_e32 v108, 3, v34
	s_mov_b32 s68, -1
	s_and_b64 s[12:13], s[6:7], vcc
	v_lshl_add_u64 v[112:113], s[14:15], 0, v[192:193]
	v_lshl_add_u64 v[114:115], v[32:33], 0, s[4:5]
	v_mov_b32_e32 v63, v62
	v_mov_b32_e32 v54, v62
	v_mov_b32_e32 v55, v62
	v_mov_b32_e32 v60, v62
	v_mov_b32_e32 v61, v62
	v_mov_b32_e32 v52, v62
	v_mov_b32_e32 v53, v62
	v_mov_b32_e32 v58, v62
	v_mov_b32_e32 v59, v62
	v_mov_b32_e32 v50, v62
	v_mov_b32_e32 v51, v62
	v_mov_b32_e32 v56, v62
	v_mov_b32_e32 v57, v62
	v_mov_b32_e32 v48, v62
	v_mov_b32_e32 v49, v62
	v_mov_b32_e32 v38, v62
	v_mov_b32_e32 v39, v62
	v_mov_b32_e32 v46, v62
	v_mov_b32_e32 v47, v62
	v_mov_b32_e32 v36, v62
	v_mov_b32_e32 v37, v62
	v_mov_b32_e32 v44, v62
	v_mov_b32_e32 v45, v62
	v_mov_b32_e32 v34, v62
	v_mov_b32_e32 v35, v62
	v_mov_b32_e32 v42, v62
	v_mov_b32_e32 v43, v62
	v_mov_b32_e32 v32, v62
	v_mov_b32_e32 v33, v62
	v_mov_b32_e32 v40, v62
	v_mov_b32_e32 v41, v62
	s_branch .LBB0_38
	s_nop 0
	s_nop 0
.LBB0_37:
	s_add_i32 s56, s56, 4
	s_cmp_ge_i32 s56, s57
	s_cbranch_scc1 .LBB0_134

.Lssd_take_pf:
	s_waitcnt vmcnt(0)
	v_mov_b32_e32 v0, v72
	v_mov_b32_e32 v1, v73
	v_mov_b32_e32 v2, v74
	v_mov_b32_e32 v3, v75
	v_mov_b32_e32 v4, v76
	v_mov_b32_e32 v5, v77
	v_mov_b32_e32 v6, v78
	v_mov_b32_e32 v7, v79
	v_mov_b32_e32 v8, v80
	v_mov_b32_e32 v9, v81
	v_mov_b32_e32 v10, v82
	v_mov_b32_e32 v11, v83
	v_mov_b32_e32 v12, v84
	v_mov_b32_e32 v13, v85
	v_mov_b32_e32 v14, v86
	v_mov_b32_e32 v15, v87
	v_mov_b32_e32 v16, v202
	v_mov_b32_e32 v17, v203
	v_mov_b32_e32 v18, v204
	v_mov_b32_e32 v19, v205
	v_mov_b32_e32 v20, v206
	v_mov_b32_e32 v21, v207
	v_mov_b32_e32 v22, v208
	v_mov_b32_e32 v23, v209
	v_mov_b32_e32 v24, v216
	v_mov_b32_e32 v25, v217
	v_mov_b32_e32 v26, v218
	v_mov_b32_e32 v27, v219
	v_mov_b32_e32 v28, v220
	v_mov_b32_e32 v29, v221
	v_mov_b32_e32 v30, v222
	v_mov_b32_e32 v31, v223
	s_or_b64 exec, exec, s[34:35]
	s_branch .LBB0_221

.LBB0_219:
	v_or_b32_e32 v68, s64, v145
	s_and_saveexec_b64 s[34:35], s[36:37]
	s_cbranch_execz .LBB0_222
	s_and_b64 vcc, exec, s[62:63]
	s_cbranch_vccz .Lssd_take_pf
	s_movk_i32 s64, 0x600
	s_waitcnt vmcnt(7)
	v_mul_lo_u32 v0, v68, s64
	v_add_lshl_u32 v192, v201, v0, 1
	s_waitcnt vmcnt(1)
	v_lshl_add_u64 v[24:25], s[60:61], 0, v[192:193]
	v_add_co_u32_e32 v8, vcc, 0x1000, v24
	global_load_dwordx4 v[0:3], v192, s[60:61]
	global_load_dwordx4 v[4:7], v192, s[60:61] offset:3072
	v_addc_co_u32_e32 v9, vcc, 0, v25, vcc
	v_add_co_u32_e32 v12, vcc, 0x2000, v24
	s_nop 1
	v_addc_co_u32_e32 v13, vcc, 0, v25, vcc
	v_add_co_u32_e32 v20, vcc, 0x3000, v24
	global_load_dwordx4 v[8:11], v[8:9], off offset:2048
	s_nop 0
	global_load_dwordx4 v[12:15], v[12:13], off offset:1024
	v_addc_co_u32_e32 v21, vcc, 0, v25, vcc
	v_add_co_u32_e32 v26, vcc, 0x4000, v24
	global_load_dwordx4 v[16:19], v[20:21], off
	s_nop 0
	global_load_dwordx4 v[20:23], v[20:21], off offset:3072
	v_addc_co_u32_e32 v27, vcc, 0, v25, vcc
	s_waitcnt vmcnt(6)
	v_add_co_u32_e32 v28, vcc, 0x5000, v24
	s_nop 1
	v_addc_co_u32_e32 v29, vcc, 0, v25, vcc
	global_load_dwordx4 v[24:27], v[26:27], off offset:2048
	s_nop 0
	global_load_dwordx4 v[28:31], v[28:29], off offset:1024
	s_or_b64 exec, exec, s[34:35]
	s_andn2_b64 vcc, exec, s[62:63]
	s_cbranch_vccz .LBB0_223

.LBB0_226:
	s_or_b64 exec, exec, s[34:35]
	s_and_b64 vcc, exec, s[62:63]
	s_cbranch_vccz .Lssd_no_pf
	v_or_b32_e32 v232, 8, v145
	s_movk_i32 s98, 0x600
	v_mul_lo_u32 v232, v232, s98
	v_add_lshl_u32 v232, v201, v232, 1
	v_add_u32_e32 v233, 0x1800, v232
	v_add_u32_e32 v234, 0x3000, v232
	v_add_u32_e32 v235, 0x4800, v232
	global_load_dwordx4 v[72:75], v232, s[60:61]
	global_load_dwordx4 v[76:79], v232, s[60:61] offset:3072
	global_load_dwordx4 v[80:83], v233, s[60:61]
	global_load_dwordx4 v[84:87], v233, s[60:61] offset:3072
	global_load_dwordx4 v[202:205], v234, s[60:61]
	global_load_dwordx4 v[206:209], v234, s[60:61] offset:3072
	global_load_dwordx4 v[216:219], v235, s[60:61]
	global_load_dwordx4 v[220:223], v235, s[60:61] offset:3072
.Lssd_no_pf:
	s_and_b64 exec, exec, s[14:15]
	s_cbranch_execz .LBB0_218
	v_mov_b32_e32 v53, 1.0
	v_mov_b32_e32 v52, v53
	s_and_saveexec_b64 s[34:35], s[10:11]
	v_sub_u32_e32 v48, 0x7f, v68
	v_cndmask_b32_e64 v48, v48, v68, s[30:31]
	v_lshl_add_u32 v48, v48, 2, 0
	v_add_u32_e32 v48, 0x20400, v48
	ds_read_b32 v52, v48
	s_or_b64 exec, exec, s[34:35]
	s_and_saveexec_b64 s[34:35], s[10:11]
	s_cbranch_execz .LBB0_231
	v_or_b32_e32 v48, 1, v68
	v_sub_u32_e32 v49, 0x7f, v48
	v_cndmask_b32_e64 v48, v49, v48, s[30:31]
	v_lshl_add_u32 v48, v48, 2, 0
	v_add_u32_e32 v48, 0x20400, v48
	ds_read_b32 v53, v48

.LBB0_243:
	s_or_b64 exec, exec, s[34:35]
	s_waitcnt vmcnt(14)
	v_lshlrev_b32_e32 v49, 16, v4
	v_lshlrev_b32_e32 v48, 16, v0
	s_waitcnt lgkmcnt(0)
	v_pk_mul_f32 v[60:61], v[52:53], v[48:49]
	s_waitcnt vmcnt(12)
	v_lshlrev_b32_e32 v49, 16, v12
	v_lshlrev_b32_e32 v48, 16, v8
	v_pk_mul_f32 v[62:63], v[54:55], v[48:49]
	s_waitcnt vmcnt(10)
	v_lshlrev_b32_e32 v49, 16, v20
	v_lshlrev_b32_e32 v48, 16, v16
	v_pk_mul_f32 v[64:65], v[56:57], v[48:49]
	s_waitcnt vmcnt(8)
	v_lshlrev_b32_e32 v49, 16, v28
	v_lshlrev_b32_e32 v48, 16, v24
	v_pk_mul_f32 v[66:67], v[58:59], v[48:49]
	s_and_b64 vcc, exec, s[54:55]
	s_cbranch_vccz .LBB0_245
	v_pk_mov_b32 v[48:49], v[66:67], v[66:67] op_sel:[1,0]
	v_pk_mov_b32 v[50:51], v[64:65], v[64:65] op_sel:[1,0]
	v_cvt_pk_bf16_f32 v48, v48, v49
	v_cvt_pk_bf16_f32 v49, v50, v51
	v_pk_mov_b32 v[50:51], v[62:63], v[62:63] op_sel:[1,0]
	s_nop 0
	v_cvt_pk_bf16_f32 v50, v50, v51
	v_mov_b32_e32 v67, v60
	v_mov_b32_e32 v66, v61
	s_cbranch_execz .LBB0_246
	s_branch .LBB0_247
